# phase C rebalanced: the 80 workgroups running the s5 chunk-state GEMM take a smaller share of the rwkv prep rows (two-pass grid stride)
# speedup vs baseline: 1.4752x; 1.0046x over previous
; __device__ __forceinline__ int tid_of(int wv) { int t = wv * 64 + lane_id(); asm volatile("" : "+v"(t)); return t; }
; __device__ __forceinline__ int bidx() { int t = blockIdx.x; asm volatile("" : "+s"(t)); return t; }
; __device__ __forceinline__ unsigned pk2(float lo, float hi) { f32x2 f; f.x = lo; f.y = hi; return __builtin_bit_cast(unsigned, __builtin_convertvector(f, bf16v2_t)); }
; __device__ __forceinline__ float bflo(unsigned u) { return __uint_as_float(u << 16); }
; __device__ __forceinline__ float bfhi(unsigned u) { return __uint_as_float(u & 0xFFFF0000u); }
; __device__ __forceinline__ float tanhf_(float x) { return 1.f - 2.f * rcpf_(1.f + __expf(2.f * x)); }
; __device__ __forceinline__ void phase_rwprep(const PP& p, int l) {
;     ...
;     const int nth = gridDim.x * 512;
;     for (int idx = bidx() * 512 + tid_of(p.wv); idx < MROWS * 112; idx += nth) {
;         const int row = idx / 112, qd = idx - row * 112, col0 = 8 * qd, zc = col0 < 768 ? col0 : col0 + 384;
;         const int b = row / TT, j = row - b * TT;
;         const bool hp = (j != 0) && (j != CTX), hn = (j != CTX - 1) && (j != TT - 1);
;         const bf16_t* q = Z + (size_t)row * ZLD + zc;
;         const u32x4 cu = *(const u32x4*)q;
;         const u32x4 pv = hp ? *(const u32x4*)(q - ZLD) : (u32x4){0u, 0u, 0u, 0u};
;         const u32x4 nx = hn ? *(const u32x4*)(q + ZLD) : (u32x4){0u, 0u, 0u, 0u};
;         const f32x4 m0 = *(const f32x4*)(mu + zc), m1 = *(const f32x4*)(mu + zc + 4);
;         const f32x4 c0 = (f32x4){bflo(cu.x), bfhi(cu.x), bflo(cu.y), bfhi(cu.y)}, c1 = (f32x4){bflo(cu.z), bfhi(cu.z), bflo(cu.w), bfhi(cu.w)};
;         const f32x4 a0 = (f32x4){bflo(pv.x), bfhi(pv.x), bflo(pv.y), bfhi(pv.y)}, a1 = (f32x4){bflo(pv.z), bfhi(pv.z), bflo(pv.w), bfhi(pv.w)};
;         const f32x4 n0 = (f32x4){bflo(nx.x), bfhi(nx.x), bflo(nx.y), bfhi(nx.y)}, n1 = (f32x4){bflo(nx.z), bfhi(nx.z), bflo(nx.w), bfhi(nx.w)};
;         f32x4 v0 = c0 + ((a0 + n0) * 0.5f - c0) * m0, v1 = c1 + ((a1 + n1) * 0.5f - c1) * m1;
;         if (col0 >= 768 && col0 < 832) {
; #pragma unroll
;             for (int i = 0; i < 4; ++i) { v0[i] = tanhf_(v0[i]); v1[i] = tanhf_(v1[i]); }
;         }
;         u32x4 o; o.x = pk2(v0[0], v0[1]); o.y = pk2(v0[2], v0[3]); o.z = pk2(v1[0], v1[1]); o.w = pk2(v1[2], v1[3]);
;         *(u32x4*)(RWP + (size_t)row * RWP_LD + col0) = o;
.LBB0_383:
	s_mov_b32 s98, 0x20000
	s_mov_b32 s99, 0x19ffff
	v_readlane_b32 s0, v254, 17
	v_readlane_b32 s6, v252, 0
	s_nop 0
	v_mov_b32_e32 v1, s0
	ds_read_b64 v[2:3], v1
	v_readlane_b32 s0, v254, 58
	v_readlane_b32 s1, v254, 59
	s_mulk_i32 s0, 0x580
	s_mov_b32 s1, s13
	v_writelane_b32 v254, s0, 62
	v_mov_b32_e32 v1, v162
	s_waitcnt lgkmcnt(0)
	v_readfirstlane_b32 s5, v3
	v_writelane_b32 v254, s1, 63
	v_lshl_add_u32 v14, s6, 9, v1
	s_mov_b32 s0, 0x39c000
	v_readfirstlane_b32 s4, v2
	v_cmp_gt_i32_e32 vcc, s0, v14
	s_and_saveexec_b64 s[0:1], vcc
	s_cbranch_execz .LBB0_392
	v_readlane_b32 s22, v254, 62
	v_readlane_b32 s23, v254, 63
	s_lshl_b64 s[22:23], s[22:23], 2
	s_add_u32 s4, s4, s22
	v_lshlrev_b32_e32 v1, 3, v1
	s_addc_u32 s5, s5, s23
	v_lshl_add_u32 v16, s6, 12, v1
	s_mov_b64 s[22:23], 0
	s_branch .LBB0_386
.LBB0_385:
	s_or_b64 exec, exec, s[24:25]
	v_cvt_pk_bf16_f32 v11, v2, v3
	v_mov_b64_e32 v[2:3], s[10:11]
	s_movk_i32 s6, 0x700
	v_mad_i64_i32 v[2:3], s[6:7], v1, s6, v[2:3]
	s_nop 0
	v_ashrrev_i32_e32 v19, 31, v18
	v_cvt_pk_bf16_f32 v8, v8, v9
	v_add_u32_e32 v14, s98, v14
	s_nop 0
	v_cmp_lt_i32_e32 vcc, s99, v14
	s_nop 0
	v_cvt_pk_bf16_f32 v9, v4, v5
	v_cvt_pk_bf16_f32 v10, v6, v7
	v_lshl_add_u64 v[2:3], v[18:19], 1, v[2:3]
	s_or_b64 s[22:23], vcc, s[22:23]
	v_lshl_add_u32 v16, s98, 3, v16
	global_store_dwordx4 v[2:3], v[8:11], off
	s_andn2_b64 exec, exec, s[22:23]
	s_cbranch_execz .LBB0_392

; __device__ __forceinline__ int lane_id() { return (int)__builtin_amdgcn_mbcnt_hi(~0u, __builtin_amdgcn_mbcnt_lo(~0u, 0u)); }
; __device__ __forceinline__ int tid_of(int wv) { int t = wv * 64 + lane_id(); asm volatile("" : "+v"(t)); return t; }
; __device__ __forceinline__ int bidx() { int t = blockIdx.x; asm volatile("" : "+s"(t)); return t; }
; __device__ __forceinline__ unsigned xb_add(unsigned* p, unsigned v) { return __hip_atomic_fetch_add(p, v, __ATOMIC_RELAXED, __HIP_MEMORY_SCOPE_AGENT); }
; __device__ __forceinline__ void xcd_barrier(const XcdBarrier& b) {
;     asm volatile("s_waitcnt vmcnt(0)" ::: "memory");
;     __syncthreads();
;     if (b.wv == 0 && lane_id() == 0) {
;         unsigned* bar = b.bar;
;         __builtin_amdgcn_s_waitcnt(0);
;         unsigned nloc = b.st[0], nx = b.st[1];
;         if (nloc == 0u) { xcd_barrier_complete(bar, b.x, nloc, nx); b.st[0] = nloc; b.st[1] = nx; }
;         const unsigned old = xb_add(&bar[XB_XSUB(b.x)], 1u);
; __device__ __forceinline__ void phase_rwprep(const PP& p, int l) {
;     ...
;     const int nth = gridDim.x * 512;
;     for (int idx = bidx() * 512 + tid_of(p.wv); idx < MROWS * 112; idx += nth) {
.LBB0_392:
	s_or_b64 exec, exec, s[0:1]
	s_cmp_eq_u32 s98, 0x20000
	s_cbranch_scc0 .Lrwp_done
	v_readlane_b32 s6, v252, 0
	s_nop 1
	s_cmpk_lt_u32 s6, 0x50
	s_cbranch_scc1 .Lrwp_done
	s_add_i32 s6, s6, 0xffffffb0
	v_mov_b32_e32 v1, v162
	v_lshl_add_u32 v14, s6, 9, v1
	v_add_u32_e32 v14, 0x1a0000, v14
	v_lshlrev_b32_e32 v16, 3, v14
	s_mov_b32 s98, 0x16000
	s_mov_b32 s99, 0x39bfff
	s_mov_b64 s[22:23], 0
	s_branch .LBB0_386
.Lrwp_done:
	s_waitcnt vmcnt(0)
	s_waitcnt vmcnt(0)
	s_barrier
	s_mov_b64 s[0:1], exec
	v_readlane_b32 s4, v252, 15
	v_readlane_b32 s5, v252, 16
	s_and_b64 s[4:5], s[0:1], s[4:5]
	s_mov_b64 exec, s[4:5]
	s_cbranch_execz .LBB0_444
	v_readlane_b32 s4, v254, 15
	s_waitcnt vmcnt(0) expcnt(0) lgkmcnt(0)
	s_nop 0
	v_mov_b32_e32 v1, s4
	ds_read_b32 v3, v1
	v_readlane_b32 s4, v254, 16
	s_waitcnt lgkmcnt(0)
	v_cmp_ne_u32_e32 vcc, 0, v3
	v_mov_b32_e32 v1, s4
	ds_read_b32 v2, v1
	s_cbranch_vccnz .LBB0_408
	s_mov_b32 s6, 1
	s_branch .LBB0_396
